# B-attention: staggered-round units start their key sweep where the leading workgroup's sweep is and wrap around (all 32 workgroups of an XCD stream K/V tiles through L2 together); on top of v21
# baseline (speedup 1.0000x reference)
; #define ATT_STAGE(t_, buf_) do { const char* gb_ = gbase + (size_t)(t_) * tstep; _Pragma("unroll") for (int j_ = 0; j_ < NPW * REP_DMA; ++j_) \
;         __builtin_amdgcn_global_load_lds((const unsigned*)(gb_ + ATT_CJ(j_ % NPW) + vbase), (LAS unsigned*)(lds + (buf_) * STAGE + (wid * NPW + j_ % NPW) * 1024), 16, 0, 0); } while (0)
; template <int DV, int NMAP> ...
;     ...
;     ATT_STAGE(T0, 0);
;     if ((wid >> 2) ^ (wid & 1)) __builtin_amdgcn_s_setprio(2);
;     for (int t = T0; t <= T1; ++t) {
; __global__ void __launch_bounds__(512, 2) trunk_fwd(Args a) {
;     ...
;                 for (int u = u0; u < 128 * 8; u += G) {
;                     const int h = u & 7, j = u >> 3, ii = j & 31, r = j >> 5;
;                     const int qblk = (r == 0) ? 127 - ii : (r == 1) ? 64 + ii : (r == 2) ? 63 - ii : ii;
;     ...
;                     att::attn_unit<256, 2>(lds, QK, VT, OB, 128 * qblk, 2 * h, 256 * h, 0, 2 * qblk + 1, false, tabB + h * 256, lam, 1.0f - li, (const float*)(ws + WS_BSUB) + (size_t)i * 256);
.LBB0_306:
	s_lshl_b32 s28, s35, 1
	s_add_i32 s28, s28, 2
	s_lshr_b32 s29, s22, 8
	s_and_b32 s29, s29, 1
	s_cbranch_scc0 .Lcy_a
	s_lshr_b32 s29, s22, 3
	s_and_b32 s29, s29, 31
	s_sub_i32 s29, 31, s29
	s_lshl_b32 s29, s29, 1
	s_cmp_lt_u32 s29, s28
	s_cselect_b32 s29, s29, 0
.Lcy_a:
	s_mov_b32 s27, s28
	s_cmp_eq_u32 s29, 0
	s_cselect_b32 s28, s28, s29
	s_lshl_b32 s4, s22, 8
	s_and_b32 s36, s4, 0x700
	v_mov_b32_e32 v0, v230
	s_movk_i32 s4, 0x100
	s_nop 0
	v_readfirstlane_b32 s20, v0
	v_cmp_gt_i32_e32 vcc, s4, v0
	s_cmpk_lt_u32 s22, 0x100
	s_cbranch_scc1 .Ltabb
	s_mov_b64 vcc, 0

; #define LAS __attribute__((address_space(3)))
; #define ATT_STAGE(t_, buf_) do { const char* gb_ = gbase + (size_t)(t_) * tstep; _Pragma("unroll") for (int j_ = 0; j_ < NPW * REP_DMA; ++j_) \
;         __builtin_amdgcn_global_load_lds((const unsigned*)(gb_ + ATT_CJ(j_ % NPW) + vbase), (LAS unsigned*)(lds + (buf_) * STAGE + (wid * NPW + j_ % NPW) * 1024), 16, 0, 0); } while (0)
; template <int DV, int NMAP> ...
;     ...
;     const int sbb = lane * 16, swz = sbb ^ (((sbb >> 9) & 1) << 5), rr = swz >> 6, cc = (swz & 63) >> 1;
;     unsigned vbase; const char* gbase; size_t tstep; const bool isk = wid < 4;
;     if (isk) { const int s = wid * NPW, mm = s >> 4, rem = s & 15, ch = rem >> 3, stt = rem & 7, R = 16 * (stt >> 1) + rr;
;         const int key = (R & ~31) + pg8::perm32(R & 31), d = 64 * ch + 32 * (stt & 1) + cc;
;         vbase = (unsigned)((key * QKLD + 2048 + (hk0 + mm) * 128 + d) * 2); gbase = (const char*)QK; tstep = (size_t)64 * QKLD * 2;
;     } else { const int s = (wid - 4) * NPW, dv = 16 * (s >> 1) + rr, key = 32 * (s & 1) + cc;
;         vbase = (unsigned)(((vrow0 + dv) * VTLD + key) * 2); gbase = (const char*)VT; tstep = (size_t)64 * 2; }
;     ...
;     const int loff = (fr * 64 + fq * 16) ^ (((fr >> 3) & 1) << 5);
;     f32x4 o[DV / 16][2];
; #pragma unroll
;     for (int db = 0; db < DV / 16; ++db) { o[db][0] = (f32x4){0.f, 0.f, 0.f, 0.f}; o[db][1] = (f32x4){0.f, 0.f, 0.f, 0.f}; }
;     float lsum[2] = {0.f, 0.f};
;     const LAS float* tab = (const LAS float*)(lds + TAB_OFF);
;     asm volatile("s_waitcnt vmcnt(0)" ::: "memory");
;     ATT_STAGE(T0, 0);
;     if ((wid >> 2) ^ (wid & 1)) __builtin_amdgcn_s_setprio(2);
;     for (int t = T0; t <= T1; ++t) {
.LBB0_315:
	s_mul_i32 s33, s29, s6
	s_add_u32 s44, s44, s33
	s_addc_u32 s45, s45, 0
	s_mul_i32 s26, s27, s6
	s_sub_u32 s26, 0, s26
	s_subb_u32 s27, 0, 0
	s_add_u32 s70, s88, s44
	s_addc_u32 s71, s89, s45
	s_lshl_b32 s34, s34, 13
	s_add_i32 s34, s34, 0
	v_lshl_add_u64 v[4:5], s[70:71], 0, v[204:205]
	s_mov_b32 m0, s34
	v_lshl_add_u64 v[6:7], v[4:5], 0, 64
	global_load_lds_dwordx4 v204, s[70:71]
	s_add_i32 m0, s34, 0x400
	v_mov_b64_e32 v[214:215], 0x400
	global_load_lds_dwordx4 v[6:7], off
	v_lshl_add_u64 v[6:7], v[4:5], 0, s[72:73]
	s_add_i32 m0, s34, 0x800
	s_nop 0
	global_load_lds_dwordx4 v[6:7], off
	v_lshl_add_u64 v[6:7], v[4:5], 0, s[68:69]
	s_add_i32 m0, s34, 0xc00
	s_nop 0
	global_load_lds_dwordx4 v[6:7], off
	v_lshl_add_u64 v[6:7], v[4:5], 0, s[38:39]
	s_add_i32 m0, s34, 0x1000
	s_nop 0
	global_load_lds_dwordx4 v[6:7], off
	v_lshl_add_u64 v[6:7], v[4:5], 0, s[16:17]
	s_add_i32 m0, s34, 0x1400
	s_nop 0
	global_load_lds_dwordx4 v[6:7], off
	v_lshl_add_u64 v[6:7], v[4:5], 0, s[10:11]
	s_add_i32 m0, s34, 0x1800
	v_lshl_add_u64 v[4:5], v[4:5], 0, s[8:9]
	global_load_lds_dwordx4 v[6:7], off
	s_add_i32 m0, s34, 0x1c00
	s_bfe_u32 s8, s20, 0x10006
	global_load_lds_dwordx4 v[4:5], off
	s_cmp_eq_u32 s21, s8
	s_cbranch_scc1 .LBB0_317
	s_setprio 2
.LBB0_317:
	s_lshr_b32 s37, s37, 6
	s_lshl_b32 s35, s35, 1
	s_lshl_b32 s57, s21, 14
	s_add_i32 s68, s37, -2
	v_bfe_u32 v236, v0, 4, 2
	v_lshlrev_b32_e32 v0, 2, v0
	s_and_b64 s[8:9], s[4:5], exec
	s_mov_b32 s69, 0x48000
	v_and_b32_e32 v0, 32, v0
	v_lshlrev_b32_e32 v3, 6, v1
	s_mov_b32 s10, 0x8040
	s_mov_b32 s16, 0x40000
	s_mov_b32 s38, 0x40040
	s_cselect_b32 s72, s69, 0x180000
	s_mov_b32 s69, 0x48040
	v_bitop3_b32 v238, v3, v0, v2 bitop3:0x36
	s_cselect_b32 s8, 0x8000, s85
	s_cselect_b32 s10, s10, 0x80040
	s_cselect_b32 s16, s16, 0x100000
	s_cselect_b32 s38, s38, 0x100040
	s_cselect_b32 s76, s69, 0x180040
	v_lshlrev_b32_e32 v0, 5, v236
	v_lshlrev_b32_e32 v1, 2, v1
	s_lshl_b32 s69, s20, 1
	s_add_i32 s52, s52, s53
	v_sub_u32_e32 v0, v0, v1
	s_and_b32 s69, s69, 0x80
	s_lshl_b32 s52, s52, 2
	v_subrev_u32_e32 v0, s69, v0
	s_and_b32 s52, s52, 0xffffff00
	s_add_i32 s69, s35, 2
	s_add_u32 s44, s44, s6
	s_addc_u32 s45, s45, s7
	s_add_u32 s44, s88, s44
	v_subrev_u32_e32 v0, s52, v0
	v_readlane_b32 s52, v255, 36
	s_addc_u32 s45, s89, s45
	v_mov_b32_e32 v12, v205
	v_mov_b32_e32 v13, v205
	v_mov_b32_e32 v14, v205
	v_mov_b32_e32 v15, v205
	s_mov_b32 s9, 0
	v_add_u32_e32 v239, s52, v0
	s_lshl_b32 s33, s29, 8
	s_nop 0
	v_add_u32_e32 v239, s33, v239
	v_lshl_add_u64 v[220:221], s[44:45], 0, v[204:205]
	v_mov_b32_e32 v204, v205
	v_mov_b64_e32 v[22:23], v[14:15]
	v_mov_b64_e32 v[26:27], v[14:15]
	v_mov_b64_e32 v[30:31], v[14:15]
	v_mov_b64_e32 v[34:35], v[14:15]
	v_mov_b64_e32 v[38:39], v[14:15]
	v_mov_b64_e32 v[42:43], v[14:15]
	v_mov_b64_e32 v[46:47], v[14:15]
	v_mov_b64_e32 v[50:51], v[14:15]
	v_mov_b64_e32 v[54:55], v[14:15]
	v_mov_b64_e32 v[58:59], v[14:15]
	v_mov_b64_e32 v[62:63], v[14:15]
	v_mov_b64_e32 v[66:67], v[14:15]
	v_mov_b64_e32 v[70:71], v[14:15]
	v_mov_b64_e32 v[74:75], v[14:15]
	v_mov_b64_e32 v[78:79], v[14:15]
	v_mov_b64_e32 v[82:83], v[14:15]
	v_mov_b64_e32 v[86:87], v[14:15]
	v_mov_b64_e32 v[90:91], v[14:15]
	v_mov_b64_e32 v[94:95], v[14:15]
	v_mov_b64_e32 v[98:99], v[14:15]
	v_mov_b64_e32 v[102:103], v[14:15]
	v_mov_b64_e32 v[106:107], v[14:15]
	v_mov_b64_e32 v[110:111], v[14:15]
	v_mov_b64_e32 v[114:115], v[14:15]
	v_mov_b64_e32 v[118:119], v[14:15]
	v_mov_b64_e32 v[122:123], v[14:15]
	v_mov_b64_e32 v[158:159], v[14:15]
	v_mov_b64_e32 v[18:19], v[14:15]
	v_mov_b64_e32 v[8:9], v[12:13]
	v_mov_b64_e32 v[4:5], v[12:13]
	v_mov_b64_e32 v[0:1], v[12:13]
	s_mov_b32 s11, s9
	s_mov_b32 s17, s9
	s_mov_b32 s39, s9
	s_mov_b32 s73, s9
	s_mov_b32 s77, s9
	v_mov_b64_e32 v[20:21], v[12:13]
	v_mov_b64_e32 v[24:25], v[12:13]
	v_mov_b64_e32 v[28:29], v[12:13]
	v_mov_b64_e32 v[32:33], v[12:13]
	v_mov_b64_e32 v[36:37], v[12:13]
	v_mov_b64_e32 v[40:41], v[12:13]
	v_mov_b64_e32 v[44:45], v[12:13]
	v_mov_b64_e32 v[48:49], v[12:13]
	v_mov_b64_e32 v[52:53], v[12:13]
	v_mov_b64_e32 v[56:57], v[12:13]
	v_mov_b64_e32 v[60:61], v[12:13]
	v_mov_b64_e32 v[64:65], v[12:13]
	v_mov_b64_e32 v[68:69], v[12:13]
	v_mov_b64_e32 v[72:73], v[12:13]
	v_mov_b64_e32 v[76:77], v[12:13]
	v_mov_b64_e32 v[80:81], v[12:13]
	v_mov_b64_e32 v[84:85], v[12:13]
	v_mov_b64_e32 v[88:89], v[12:13]
	v_mov_b64_e32 v[92:93], v[12:13]
	v_mov_b64_e32 v[96:97], v[12:13]
	v_mov_b64_e32 v[100:101], v[12:13]
	v_mov_b64_e32 v[104:105], v[12:13]
	v_mov_b64_e32 v[108:109], v[12:13]
	v_mov_b64_e32 v[112:113], v[12:13]
	v_mov_b64_e32 v[116:117], v[12:13]
	v_mov_b64_e32 v[120:121], v[12:13]
	v_mov_b64_e32 v[156:157], v[12:13]
	v_mov_b64_e32 v[16:17], v[12:13]
	v_mov_b64_e32 v[10:11], v[14:15]
	v_mov_b64_e32 v[6:7], v[14:15]
	v_mov_b64_e32 v[2:3], v[14:15]
	s_mov_b32 s84, s29
	s_mov_b32 s32, 0
	v_mov_b64_e32 v[218:219], v[204:205]
	s_waitcnt vmcnt(0)
	s_branch .LBB0_320
; template <int DV, int NMAP> ...
;     ...
;             bf16x8 pf[2][2];
; #pragma unroll
;             for (int qb = 0; qb < 2; ++qb) {
; #pragma unroll
;                 for (int kb = 0; kb < 2; ++kb)
; #pragma unroll
;                     for (int i = 0; i < 4; ++i) s[kb][qb][i] = __builtin_amdgcn_exp2f(s[kb][qb][i]);
;                 v4u w; w.x = pg8::cvt_pk_bf16(s[0][qb][0], s[0][qb][1]); w.y = pg8::cvt_pk_bf16(s[0][qb][2], s[0][qb][3]);
;                 w.z = pg8::cvt_pk_bf16(s[1][qb][0], s[1][qb][1]); w.w = pg8::cvt_pk_bf16(s[1][qb][2], s[1][qb][3]); pf[qb][0] = __builtin_bit_cast(bf16x8, w);
;                 pf[qb][1] = pf[qb][0];
;             }
;             __builtin_amdgcn_sched_barrier(0);
; #pragma unroll
;             for (int i = 0; i < 2 * (DV / 16); ++i) {
;                 constexpr int NV = 2 * (DV / 16), EPS = 16 / (NV / 2);
;                 if (i == NV / 2) {
; #pragma unroll
;                     for (int qb = 0; qb < 2; ++qb) {
;                         v4u w; w.x = pg8::cvt_pk_bf16(s[2][qb][0], s[2][qb][1]); w.y = pg8::cvt_pk_bf16(s[2][qb][2], s[2][qb][3]);
;                         w.z = pg8::cvt_pk_bf16(s[3][qb][0], s[3][qb][1]); w.w = pg8::cvt_pk_bf16(s[3][qb][2], s[3][qb][3]); pf[qb][1] = __builtin_bit_cast(bf16x8, w);
;                         const f32x4 pa = (s[0][qb] + s[1][qb]) + (s[2][qb] + s[3][qb]);
;                         lsum[qb] += (pa[0] + pa[1]) + (pa[2] + pa[3]);
;                     }
;                 }
;                 bf16x8 cur = v0; v0 = v1; v1 = v2; if (i + 3 < NV) v2 = ATT_VLD(i + 3);
;                 if (i + 3 < NV) lgkm_pin<3>(cur); else if (i + 2 < NV) lgkm_pin<2>(cur); else if (i + 1 < NV) lgkm_pin<1>(cur); else lgkm_pin<0>(cur);
;                 __builtin_amdgcn_sched_barrier(0);
;                 o[i % (DV / 16)][0] = __builtin_amdgcn_mfma_f32_16x16x32_bf16(cur, pf[0][i / (DV / 16)], o[i % (DV / 16)][0], 0, 0, 0);
;                 o[i % (DV / 16)][1] = __builtin_amdgcn_mfma_f32_16x16x32_bf16(cur, pf[1][i / (DV / 16)], o[i % (DV / 16)][1], 0, 0, 0);
;                 if (i < NV / 2) {
; #pragma unroll
;                     for (int r_ = 0; r_ < EPS; ++r_) { const int e_ = i * EPS + r_; s[2 + (e_ >> 3)][(e_ >> 2) & 1][e_ & 3] = __builtin_amdgcn_exp2f(s[2 + (e_ >> 3)][(e_ >> 2) & 1][e_ & 3]); }
;                 }
;                 __builtin_amdgcn_sched_barrier(0);
;             }
.LBB0_318:
	v_exp_f32_e32 v222, v196
	v_exp_f32_e32 v223, v197
	v_exp_f32_e32 v196, v198
	v_exp_f32_e32 v197, v199
	v_exp_f32_e32 v198, v188
	v_exp_f32_e32 v199, v189
	v_exp_f32_e32 v190, v190
	v_exp_f32_e32 v191, v191
	v_cvt_pk_bf16_f32 v206, v222, v223
	v_cvt_pk_bf16_f32 v207, v196, v197
	v_cvt_pk_bf16_f32 v208, v198, v199
	v_cvt_pk_bf16_f32 v209, v190, v191
	v_exp_f32_e32 v188, v180
	v_exp_f32_e32 v189, v181
	v_exp_f32_e32 v180, v182
	v_exp_f32_e32 v181, v183
	v_exp_f32_e32 v182, v176
	v_exp_f32_e32 v183, v177
	v_exp_f32_e32 v176, v178
	v_exp_f32_e32 v177, v179
	v_cvt_pk_bf16_f32 v240, v188, v189
	v_cvt_pk_bf16_f32 v241, v180, v181
	v_cvt_pk_bf16_f32 v242, v182, v183
	v_cvt_pk_bf16_f32 v243, v176, v177
	ds_read_b128 v[244:247], v204 offset:0x1800
	s_waitcnt lgkmcnt(3)
	v_mfma_f32_16x16x32_bf16 v[156:159], v[200:203], v[206:209], v[156:159]
	v_exp_f32_e32 v178, v172
	v_mfma_f32_16x16x32_bf16 v[120:123], v[200:203], v[240:243], v[120:123]
	ds_read_b128 v[200:203], v204 offset:0x2000
	s_waitcnt lgkmcnt(3)
	v_mfma_f32_16x16x32_bf16 v[116:119], v[192:195], v[206:209], v[116:119]
	v_exp_f32_e32 v179, v173
	v_mfma_f32_16x16x32_bf16 v[112:115], v[192:195], v[240:243], v[112:115]
	ds_read_b128 v[192:195], v204 offset:0x2800
	s_waitcnt lgkmcnt(3)
	v_mfma_f32_16x16x32_bf16 v[108:111], v[184:187], v[206:209], v[108:111]
	v_exp_f32_e32 v248, v174
	v_mfma_f32_16x16x32_bf16 v[104:107], v[184:187], v[240:243], v[104:107]
	ds_read_b128 v[184:187], v204 offset:0x3000
	s_waitcnt lgkmcnt(3)
	v_mfma_f32_16x16x32_bf16 v[100:103], v[244:247], v[206:209], v[100:103]
	v_exp_f32_e32 v249, v175
	v_mfma_f32_16x16x32_bf16 v[96:99], v[244:247], v[240:243], v[96:99]
	ds_read_b128 v[172:175], v204 offset:0x3800
	s_waitcnt lgkmcnt(3)
	v_mfma_f32_16x16x32_bf16 v[92:95], v[200:203], v[206:209], v[92:95]
	v_exp_f32_e32 v244, v168
	v_mfma_f32_16x16x32_bf16 v[88:91], v[200:203], v[240:243], v[88:91]
	ds_read_b128 v[200:203], v204 offset:0x4000
	s_waitcnt lgkmcnt(3)
	v_mfma_f32_16x16x32_bf16 v[84:87], v[192:195], v[206:209], v[84:87]
	v_exp_f32_e32 v245, v169
	v_mfma_f32_16x16x32_bf16 v[80:83], v[192:195], v[240:243], v[80:83]
	ds_read_b128 v[192:195], v204 offset:0x4800
	s_waitcnt lgkmcnt(3)
	v_mfma_f32_16x16x32_bf16 v[76:79], v[184:187], v[206:209], v[76:79]
	v_exp_f32_e32 v246, v170
	v_mfma_f32_16x16x32_bf16 v[72:75], v[184:187], v[240:243], v[72:75]
	ds_read_b128 v[184:187], v204 offset:0x5000
	s_waitcnt lgkmcnt(3)
	v_mfma_f32_16x16x32_bf16 v[68:71], v[172:175], v[206:209], v[68:71]
	v_exp_f32_e32 v247, v171
	v_mfma_f32_16x16x32_bf16 v[64:67], v[172:175], v[240:243], v[64:67]
	ds_read_b128 v[168:171], v204 offset:0x5800
	s_waitcnt lgkmcnt(3)
	v_mfma_f32_16x16x32_bf16 v[60:63], v[200:203], v[206:209], v[60:63]
	v_mfma_f32_16x16x32_bf16 v[56:59], v[200:203], v[240:243], v[56:59]
	v_exp_f32_e32 v200, v164
	ds_read_b128 v[172:175], v204 offset:0x6000
	s_waitcnt lgkmcnt(3)
	v_mfma_f32_16x16x32_bf16 v[52:55], v[192:195], v[206:209], v[52:55]
	v_exp_f32_e32 v201, v165
	v_mfma_f32_16x16x32_bf16 v[48:51], v[192:195], v[240:243], v[48:51]
	ds_read_b128 v[192:195], v204 offset:0x6800
	s_waitcnt lgkmcnt(3)
	v_mfma_f32_16x16x32_bf16 v[44:47], v[184:187], v[206:209], v[44:47]
	v_exp_f32_e32 v202, v166
	v_mfma_f32_16x16x32_bf16 v[40:43], v[184:187], v[240:243], v[40:43]
	ds_read_b128 v[184:187], v204 offset:0x7000
	s_waitcnt lgkmcnt(3)
	v_mfma_f32_16x16x32_bf16 v[36:39], v[168:171], v[206:209], v[36:39]
	v_exp_f32_e32 v203, v167
	v_mfma_f32_16x16x32_bf16 v[32:35], v[168:171], v[240:243], v[32:35]
	ds_read_b128 v[164:167], v204 offset:0x7800
	s_waitcnt lgkmcnt(3)
	v_mfma_f32_16x16x32_bf16 v[28:31], v[172:175], v[206:209], v[28:31]
	v_exp_f32_e32 v250, v160
	v_mfma_f32_16x16x32_bf16 v[24:27], v[172:175], v[240:243], v[24:27]
	ds_read_b128 v[168:171], v204 offset:0x400
	s_waitcnt lgkmcnt(3)
	v_mfma_f32_16x16x32_bf16 v[20:23], v[192:195], v[206:209], v[20:23]
	v_exp_f32_e32 v251, v161
	v_mfma_f32_16x16x32_bf16 v[12:15], v[192:195], v[240:243], v[12:15]
	ds_read_b128 v[172:175], v204 offset:0xc00
	s_waitcnt lgkmcnt(3)
	v_mfma_f32_16x16x32_bf16 v[16:19], v[184:187], v[206:209], v[16:19]
	v_exp_f32_e32 v192, v162
	v_mfma_f32_16x16x32_bf16 v[8:11], v[184:187], v[240:243], v[8:11]
	ds_read_b128 v[184:187], v204 offset:0x1400
	s_waitcnt lgkmcnt(3)
	v_mfma_f32_16x16x32_bf16 v[4:7], v[164:167], v[206:209], v[4:7]
	v_exp_f32_e32 v193, v163
	v_mfma_f32_16x16x32_bf16 v[0:3], v[164:167], v[240:243], v[0:3]
	v_add_f32_e64 v164, v198, v222
	v_add_f32_e64 v165, v199, v223
	v_pk_add_f32 v[166:167], v[190:191], v[196:197]
	v_cvt_pk_bf16_f32 v196, v178, v179
	v_pk_add_f32 v[178:179], v[200:201], v[178:179]
	v_pk_add_f32 v[190:191], v[202:203], v[248:249]
	v_pk_add_f32 v[182:183], v[182:183], v[188:189]
	v_pk_add_f32 v[176:177], v[176:177], v[180:181]
	v_pk_add_f32 v[180:181], v[250:251], v[244:245]
	v_pk_add_f32 v[188:189], v[192:193], v[246:247]
	v_pk_add_f32 v[190:191], v[190:191], v[166:167]
	v_pk_add_f32 v[178:179], v[178:179], v[164:165]
	v_pk_add_f32 v[176:177], v[188:189], v[176:177]
	v_pk_add_f32 v[180:181], v[180:181], v[182:183]
	v_mov_b32_e32 v183, v178
	v_mov_b32_e32 v182, v180
	v_mov_b32_e32 v178, v181
	v_mov_b32_e32 v180, v176
	v_mov_b32_e32 v181, v190
	v_mov_b32_e32 v190, v177
	v_pk_add_f32 v[178:179], v[182:183], v[178:179]
	v_pk_add_f32 v[176:177], v[180:181], v[190:191]
	v_cvt_pk_bf16_f32 v197, v248, v249
	v_cvt_pk_bf16_f32 v198, v200, v201
	v_cvt_pk_bf16_f32 v199, v202, v203
	v_cvt_pk_bf16_f32 v200, v244, v245
	v_cvt_pk_bf16_f32 v201, v246, v247
	s_nop 0
	v_pk_add_f32 v[176:177], v[178:179], v[176:177]
	v_cvt_pk_bf16_f32 v202, v250, v251
	v_cvt_pk_bf16_f32 v203, v192, v193
	s_nop 0
	v_pk_add_f32 v[218:219], v[218:219], v[176:177]
	ds_read_b128 v[176:179], v204 offset:0x1c00
	s_waitcnt lgkmcnt(3)
; __device__ __forceinline__ unsigned cvt_pk_bf16(float lo, float hi) { unsigned r; asm volatile("v_cvt_pk_bf16_f32 %0, %1, %2" : "=v"(r) : "v"(lo), "v"(hi)); return r; }
; template <int N> __device__ __forceinline__ void lgkm_pin(bf16x8& f) { (void)f; asm volatile("s_waitcnt lgkmcnt(%0)" :: "n"(N) : "memory"); }
; template <int DV, int NMAP> ...
;     ...
;     for (int t = T0; t <= T1; ++t) {
;         const int cur = (t - T0) & 1;
;         asm volatile("s_waitcnt vmcnt(0)" ::: "memory");
;         asm volatile("s_waitcnt lgkmcnt(0)" ::: "memory"); __builtin_amdgcn_s_barrier(); asm volatile("" ::: "memory");
;         const bool inr = (t >= lo_w && t <= cw);
;         if (t < T1 && (isk || !inr)) ATT_STAGE(t + 1, cur ^ 1);
;     ...
;             for (int i = 0; i < 2 * (DV / 16); ++i) {
;                 constexpr int NV = 2 * (DV / 16), EPS = 16 / (NV / 2);
;                 if (i == NV / 2) {
; #pragma unroll
;                     for (int qb = 0; qb < 2; ++qb) {
;                         v4u w; w.x = pg8::cvt_pk_bf16(s[2][qb][0], s[2][qb][1]); w.y = pg8::cvt_pk_bf16(s[2][qb][2], s[2][qb][3]);
;                         w.z = pg8::cvt_pk_bf16(s[3][qb][0], s[3][qb][1]); w.w = pg8::cvt_pk_bf16(s[3][qb][2], s[3][qb][3]); pf[qb][1] = __builtin_bit_cast(bf16x8, w);
;                         const f32x4 pa = (s[0][qb] + s[1][qb]) + (s[2][qb] + s[3][qb]);
;                         lsum[qb] += (pa[0] + pa[1]) + (pa[2] + pa[3]);
;                     }
;                 }
;                 bf16x8 cur = v0; v0 = v1; v1 = v2; if (i + 3 < NV) v2 = ATT_VLD(i + 3);
;                 if (i + 3 < NV) lgkm_pin<3>(cur); else if (i + 2 < NV) lgkm_pin<2>(cur); else if (i + 1 < NV) lgkm_pin<1>(cur); else lgkm_pin<0>(cur);
;                 __builtin_amdgcn_sched_barrier(0);
;                 o[i % (DV / 16)][0] = __builtin_amdgcn_mfma_f32_16x16x32_bf16(cur, pf[0][i / (DV / 16)], o[i % (DV / 16)][0], 0, 0, 0);
;                 o[i % (DV / 16)][1] = __builtin_amdgcn_mfma_f32_16x16x32_bf16(cur, pf[1][i / (DV / 16)], o[i % (DV / 16)][1], 0, 0, 0);
;                 if (i < NV / 2) {
; #pragma unroll
;                     for (int r_ = 0; r_ < EPS; ++r_) { const int e_ = i * EPS + r_; s[2 + (e_ >> 3)][(e_ >> 2) & 1][e_ & 3] = __builtin_amdgcn_exp2f(s[2 + (e_ >> 3)][(e_ >> 2) & 1][e_ & 3]); }
;                 }
;                 __builtin_amdgcn_sched_barrier(0);
;             }
	v_mfma_f32_16x16x32_bf16 v[156:159], v[168:171], v[196:199], v[156:159]
	v_mfma_f32_16x16x32_bf16 v[120:123], v[168:171], v[200:203], v[120:123]
	ds_read_b128 v[168:171], v204 offset:0x2400
	s_waitcnt lgkmcnt(3)
	v_mfma_f32_16x16x32_bf16 v[116:119], v[172:175], v[196:199], v[116:119]
	v_mfma_f32_16x16x32_bf16 v[112:115], v[172:175], v[200:203], v[112:115]
	ds_read_b128 v[172:175], v204 offset:0x2c00
	s_waitcnt lgkmcnt(3)
	v_mfma_f32_16x16x32_bf16 v[108:111], v[184:187], v[196:199], v[108:111]
	v_mfma_f32_16x16x32_bf16 v[104:107], v[184:187], v[200:203], v[104:107]
	ds_read_b128 v[180:183], v204 offset:0x3400
	s_waitcnt lgkmcnt(3)
	v_mfma_f32_16x16x32_bf16 v[100:103], v[176:179], v[196:199], v[100:103]
	v_mfma_f32_16x16x32_bf16 v[96:99], v[176:179], v[200:203], v[96:99]
	ds_read_b128 v[176:179], v204 offset:0x3c00
	s_waitcnt lgkmcnt(3)
	v_mfma_f32_16x16x32_bf16 v[92:95], v[168:171], v[196:199], v[92:95]
	v_mfma_f32_16x16x32_bf16 v[88:91], v[168:171], v[200:203], v[88:91]
	ds_read_b128 v[168:171], v204 offset:0x4400
	s_waitcnt lgkmcnt(3)
	v_mfma_f32_16x16x32_bf16 v[84:87], v[172:175], v[196:199], v[84:87]
	v_mfma_f32_16x16x32_bf16 v[80:83], v[172:175], v[200:203], v[80:83]
	ds_read_b128 v[172:175], v204 offset:0x4c00
	s_waitcnt lgkmcnt(3)
	v_mfma_f32_16x16x32_bf16 v[76:79], v[180:183], v[196:199], v[76:79]
	v_mfma_f32_16x16x32_bf16 v[72:75], v[180:183], v[200:203], v[72:75]
	ds_read_b128 v[180:183], v204 offset:0x5400
	ds_read_b128 v[184:187], v204 offset:0x6c00
	s_waitcnt lgkmcnt(4)
	v_mfma_f32_16x16x32_bf16 v[68:71], v[176:179], v[196:199], v[68:71]
	v_mfma_f32_16x16x32_bf16 v[64:67], v[176:179], v[200:203], v[64:67]
	ds_read_b128 v[176:179], v204 offset:0x5c00
	ds_read_b128 v[188:191], v204 offset:0x7400
	s_waitcnt lgkmcnt(5)
	v_mfma_f32_16x16x32_bf16 v[60:63], v[168:171], v[196:199], v[60:63]
	v_mfma_f32_16x16x32_bf16 v[56:59], v[168:171], v[200:203], v[56:59]
	ds_read_b128 v[168:171], v204 offset:0x6400
	ds_read_b128 v[192:195], v204 offset:0x7c00
	s_waitcnt lgkmcnt(6)
	v_mfma_f32_16x16x32_bf16 v[52:55], v[172:175], v[196:199], v[52:55]
	v_mfma_f32_16x16x32_bf16 v[48:51], v[172:175], v[200:203], v[48:51]
	s_waitcnt lgkmcnt(5)
	v_mfma_f32_16x16x32_bf16 v[44:47], v[180:183], v[196:199], v[44:47]
	v_mfma_f32_16x16x32_bf16 v[40:43], v[180:183], v[200:203], v[40:43]
	s_waitcnt lgkmcnt(3)
	v_mfma_f32_16x16x32_bf16 v[36:39], v[176:179], v[196:199], v[36:39]
	v_mfma_f32_16x16x32_bf16 v[32:35], v[176:179], v[200:203], v[32:35]
	s_waitcnt lgkmcnt(1)
	v_mfma_f32_16x16x32_bf16 v[28:31], v[168:171], v[196:199], v[28:31]
	v_mfma_f32_16x16x32_bf16 v[24:27], v[168:171], v[200:203], v[24:27]
	s_mov_b32 s32, 1
.LBB0_319:
	s_add_i32 s84, s84, 1
	v_add_u32_e32 v239, 0x100, v239
	v_lshl_add_u64 v[220:221], v[220:221], 0, s[6:7]
	s_add_i32 s53, s84, 1
	s_cmp_lg_u32 s53, s69
	s_cbranch_scc1 .Lcy_1
	v_lshl_add_u64 v[220:221], v[220:221], 0, s[26:27]
.Lcy_1:
	s_cmp_lg_u32 s84, s69
	s_cbranch_scc1 .Lcy_2
	s_cmp_eq_u32 s29, 0
	s_cbranch_scc1 .LBB0_327
	s_mov_b32 s84, 0
	s_lshl_b32 s53, s69, 8
	s_nop 0
	v_subrev_u32_e32 v239, s53, v239
.Lcy_2:
	s_cmp_eq_u32 s84, s29
	s_cbranch_scc1 .LBB0_327
.LBB0_320:
	s_and_b32 s52, s84, 1
	s_cmp_le_u32 s84, s37
	s_cselect_b64 s[44:45], -1, 0
	s_cmp_gt_u32 s84, s37
	s_waitcnt vmcnt(0)
	s_cselect_b64 s[70:71], -1, 0
	s_add_i32 s53, s84, 1
	s_cmp_lg_u32 s53, s28
	s_waitcnt lgkmcnt(0)
	s_barrier
	s_cselect_b64 s[78:79], -1, 0
	s_or_b64 s[70:71], s[4:5], s[70:71]
	s_and_b64 s[70:71], s[78:79], s[70:71]
	s_andn2_b64 vcc, exec, s[70:71]
	s_cbranch_vccnz .LBB0_322
	s_lshl_b32 s53, s52, 16
	s_xor_b32 s53, s53, 0x10000
	s_add_i32 s53, s34, s53
	s_mov_b32 m0, s53
	v_lshl_add_u64 v[160:161], v[220:221], 0, 64
	global_load_lds_dwordx4 v[220:221], off
	s_add_i32 m0, s53, 0x400
	s_nop 0
	global_load_lds_dwordx4 v[160:161], off
	v_lshl_add_u64 v[160:161], v[220:221], 0, s[8:9]
	s_add_i32 m0, s53, 0x800
	s_nop 0
	global_load_lds_dwordx4 v[160:161], off
	v_lshl_add_u64 v[160:161], v[220:221], 0, s[10:11]
	s_add_i32 m0, s53, 0xc00
	s_nop 0
	global_load_lds_dwordx4 v[160:161], off
	v_lshl_add_u64 v[160:161], v[220:221], 0, s[16:17]
	s_add_i32 m0, s53, 0x1000
	s_nop 0
	global_load_lds_dwordx4 v[160:161], off
	v_lshl_add_u64 v[160:161], v[220:221], 0, s[38:39]
	s_add_i32 m0, s53, 0x1400
	s_nop 0
	global_load_lds_dwordx4 v[160:161], off
	v_lshl_add_u64 v[160:161], v[220:221], 0, s[72:73]
	s_add_i32 m0, s53, 0x1800
	s_nop 0
	global_load_lds_dwordx4 v[160:161], off
	v_lshl_add_u64 v[160:161], v[220:221], 0, s[76:77]
	s_add_i32 m0, s53, 0x1c00
	s_nop 0
	global_load_lds_dwordx4 v[160:161], off
; #define LAS __attribute__((address_space(3)))
; template <int N> __device__ __forceinline__ void lgkm_pin(bf16x8& f) { (void)f; asm volatile("s_waitcnt lgkmcnt(%0)" :: "n"(N) : "memory"); }
; #define ATT_STAGE(t_, buf_) do { const char* gb_ = gbase + (size_t)(t_) * tstep; _Pragma("unroll") for (int j_ = 0; j_ < NPW * REP_DMA; ++j_) \
;         __builtin_amdgcn_global_load_lds((const unsigned*)(gb_ + ATT_CJ(j_ % NPW) + vbase), (LAS unsigned*)(lds + (buf_) * STAGE + (wid * NPW + j_ % NPW) * 1024), 16, 0, 0); } while (0)
; #define ATT_KLD(i_) lds_rd(stk, (((i_) >> 2) >> 1) * 8192 + (((i_) & 3) * 2 + (((i_) >> 2) & 1)) * 1024)
; template <int DV, int NMAP> ...
;     ...
;             const LAS unsigned char* st = lds + cur * STAGE;
;             f32x4 s[4][2];
; #pragma unroll
;             for (int kb = 0; kb < 4; ++kb) { s[kb][0] = (f32x4){0.f, 0.f, 0.f, 0.f}; s[kb][1] = (f32x4){0.f, 0.f, 0.f, 0.f}; }
;             const unsigned stk = (unsigned)(size_t)(st + mp * 16384 + loff), stv = (unsigned)(size_t)(st + NMAP * 16384 + loff);
;     ...
;             { bf16x8 f0 = ATT_KLD(0), f1 = ATT_KLD(1), f2 = ATT_KLD(2);
; #pragma unroll
;               for (int i = 0; i < 16; ++i) {
;                   bf16x8 cur = f0; f0 = f1; f1 = f2; if (i + 3 < 16) f2 = ATT_KLD(i + 3);
;                   if (i + 3 < 16) lgkm_pin<3>(cur); else if (i + 2 < 16) lgkm_pin<2>(cur); else if (i + 1 < 16) lgkm_pin<1>(cur); else lgkm_pin<0>(cur);
;                   __builtin_amdgcn_sched_barrier(0);
;                   s[i & 3][0] = __builtin_amdgcn_mfma_f32_16x16x32_bf16(cur, q[0][i >> 2], s[i & 3][0], 0, 0, 0);
;                   s[i & 3][1] = __builtin_amdgcn_mfma_f32_16x16x32_bf16(cur, q[1][i >> 2], s[i & 3][1], 0, 0, 0);
;                   __builtin_amdgcn_sched_barrier(0);
;               } }
;             if (t < T1 && !isk) ATT_STAGE(t + 1, cur ^ 1);
.LBB0_322:
	s_andn2_b64 vcc, exec, s[44:45]
	s_cbranch_vccnz .Lbt_skip
	s_lshl_b32 s45, s52, 16
	s_add_i32 s44, s45, 0
	s_add_i32 s52, s44, s57
	v_add_u32_e32 v204, s52, v238
	ds_read_b128 v[160:163], v204 offset:0
	ds_read_b128 v[164:167], v204 offset:0x800
	ds_read_b128 v[168:171], v204 offset:0x1000
	ds_read_b128 v[172:175], v204 offset:0x1800
	s_cmp_eq_u32 s32, 1
	s_cbranch_scc0 .Lbt_qk
	v_mfma_f32_16x16x32_bf16 v[20:23], v[184:187], v[196:199], v[20:23]
	v_mfma_f32_16x16x32_bf16 v[12:15], v[184:187], v[200:203], v[12:15]
	v_mfma_f32_16x16x32_bf16 v[16:19], v[188:191], v[196:199], v[16:19]
	v_mfma_f32_16x16x32_bf16 v[8:11], v[188:191], v[200:203], v[8:11]
	v_mfma_f32_16x16x32_bf16 v[4:7], v[192:195], v[196:199], v[4:7]
	v_mfma_f32_16x16x32_bf16 v[0:3], v[192:195], v[200:203], v[0:3]
	s_mov_b32 s32, 0
.Lbt_qk:
	s_waitcnt lgkmcnt(3)
	s_nop 0
	v_mfma_f32_16x16x32_bf16 v[176:179], v[160:163], v[124:127], 0
	v_mfma_f32_16x16x32_bf16 v[160:163], v[160:163], v[140:143], 0
	ds_read_b128 v[180:183], v204 offset:0x400
	s_waitcnt lgkmcnt(3)
	v_mfma_f32_16x16x32_bf16 v[184:187], v[164:167], v[124:127], 0
	v_mfma_f32_16x16x32_bf16 v[164:167], v[164:167], v[140:143], 0
	ds_read_b128 v[188:191], v204 offset:0xc00
	s_waitcnt lgkmcnt(3)
	v_mfma_f32_16x16x32_bf16 v[192:195], v[168:171], v[124:127], 0
	v_mfma_f32_16x16x32_bf16 v[168:171], v[168:171], v[140:143], 0
	ds_read_b128 v[196:199], v204 offset:0x1400
	s_waitcnt lgkmcnt(3)
	v_mfma_f32_16x16x32_bf16 v[200:203], v[172:175], v[124:127], 0
	v_mfma_f32_16x16x32_bf16 v[172:175], v[172:175], v[140:143], 0
	ds_read_b128 v[240:243], v204 offset:0x1c00
	s_waitcnt lgkmcnt(3)
	v_mfma_f32_16x16x32_bf16 v[176:179], v[180:183], v[128:131], v[176:179]
	v_mfma_f32_16x16x32_bf16 v[160:163], v[180:183], v[144:147], v[160:163]
	ds_read_b128 v[180:183], v204 offset:0x2000
	s_waitcnt lgkmcnt(3)
	v_mfma_f32_16x16x32_bf16 v[164:167], v[188:191], v[144:147], v[164:167]
	v_mfma_f32_16x16x32_bf16 v[184:187], v[188:191], v[128:131], v[184:187]
	ds_read_b128 v[188:191], v204 offset:0x2800
	s_waitcnt lgkmcnt(3)
	v_mfma_f32_16x16x32_bf16 v[168:171], v[196:199], v[144:147], v[168:171]
	v_mfma_f32_16x16x32_bf16 v[192:195], v[196:199], v[128:131], v[192:195]
	ds_read_b128 v[196:199], v204 offset:0x3000
	s_waitcnt lgkmcnt(3)
	v_mfma_f32_16x16x32_bf16 v[172:175], v[240:243], v[144:147], v[172:175]
	v_mfma_f32_16x16x32_bf16 v[200:203], v[240:243], v[128:131], v[200:203]
	ds_read_b128 v[240:243], v204 offset:0x3800
	s_waitcnt lgkmcnt(3)
	v_mfma_f32_16x16x32_bf16 v[176:179], v[180:183], v[132:135], v[176:179]
	v_mfma_f32_16x16x32_bf16 v[160:163], v[180:183], v[148:151], v[160:163]
	ds_read_b128 v[180:183], v204 offset:0x2400
	s_waitcnt lgkmcnt(3)
	v_mfma_f32_16x16x32_bf16 v[164:167], v[188:191], v[148:151], v[164:167]
	v_mfma_f32_16x16x32_bf16 v[184:187], v[188:191], v[132:135], v[184:187]
	ds_read_b128 v[244:247], v204 offset:0x2c00
	s_waitcnt lgkmcnt(3)
	v_mfma_f32_16x16x32_bf16 v[168:171], v[196:199], v[148:151], v[168:171]
	v_mfma_f32_16x16x32_bf16 v[192:195], v[196:199], v[132:135], v[192:195]
	ds_read_b128 v[248:251], v204 offset:0x3400
	s_waitcnt lgkmcnt(3)
	v_mfma_f32_16x16x32_bf16 v[200:203], v[240:243], v[132:135], v[200:203]
	v_mfma_f32_16x16x32_bf16 v[240:243], v[240:243], v[148:151], v[172:175]
	ds_read_b128 v[206:209], v204 offset:0x3c00
	s_waitcnt lgkmcnt(3)
	v_mfma_f32_16x16x32_bf16 v[196:199], v[180:183], v[136:139], v[176:179]
	v_mfma_f32_16x16x32_bf16 v[180:183], v[180:183], v[152:155], v[160:163]
	s_waitcnt lgkmcnt(2)
	v_mfma_f32_16x16x32_bf16 v[188:191], v[244:247], v[136:139], v[184:187]
	v_mfma_f32_16x16x32_bf16 v[176:179], v[244:247], v[152:155], v[164:167]
	s_waitcnt lgkmcnt(1)
	v_mfma_f32_16x16x32_bf16 v[172:175], v[248:251], v[136:139], v[192:195]
	v_mfma_f32_16x16x32_bf16 v[168:171], v[248:251], v[152:155], v[168:171]
	s_waitcnt lgkmcnt(0)
	v_mfma_f32_16x16x32_bf16 v[164:167], v[206:209], v[136:139], v[200:203]
	v_mfma_f32_16x16x32_bf16 v[160:163], v[206:209], v[152:155], v[240:243]
	s_add_i32 s53, s84, 1
	s_cmp_eq_u32 s53, s28
	s_cselect_b64 s[52:53], -1, 0
	s_or_b64 s[52:53], s[4:5], s[52:53]
	s_and_b64 vcc, exec, s[52:53]
	s_cbranch_vccnz .LBB0_325
	s_xor_b32 s45, s45, 0x10000
	s_add_i32 s45, s34, s45
	s_mov_b32 m0, s45
	v_lshl_add_u64 v[184:185], v[220:221], 0, 64
	global_load_lds_dwordx4 v[220:221], off
	s_add_i32 m0, s45, 0x400
	s_mov_b64 s[52:53], 0x100040
	global_load_lds_dwordx4 v[184:185], off
	v_lshl_add_u64 v[184:185], v[220:221], 0, s[24:25]
	s_add_i32 m0, s45, 0x800
	s_nop 0
	global_load_lds_dwordx4 v[184:185], off
	v_lshl_add_u64 v[184:185], v[220:221], 0, s[12:13]
	s_add_i32 m0, s45, 0xc00
	s_nop 0
	global_load_lds_dwordx4 v[184:185], off
	v_lshl_add_u64 v[184:185], v[220:221], 0, s[30:31]
	s_add_i32 m0, s45, 0x1000
	s_nop 0
	global_load_lds_dwordx4 v[184:185], off
	v_lshl_add_u64 v[184:185], v[220:221], 0, s[52:53]
	s_add_i32 m0, s45, 0x1400
	s_mov_b64 s[52:53], 0x180000
	global_load_lds_dwordx4 v[184:185], off
	v_lshl_add_u64 v[184:185], v[220:221], 0, s[52:53]
	s_add_i32 m0, s45, 0x1800
	s_mov_b64 s[52:53], 0x180040
	global_load_lds_dwordx4 v[184:185], off
	v_lshl_add_u64 v[184:185], v[220:221], 0, s[52:53]
	s_add_i32 m0, s45, 0x1c00
	s_nop 0
	global_load_lds_dwordx4 v[184:185], off

; template <int N> __device__ __forceinline__ void lgkm_pin(bf16x8& f) { (void)f; asm volatile("s_waitcnt lgkmcnt(%0)" :: "n"(N) : "memory"); }
; #define ATT_VLD(i_) lds_rd(stv, ((((i_) % (DV / 16)) * 2) + ((i_) / (DV / 16))) * 1024)
; template <int DV, int NMAP> ...
;     ...
;                 bf16x8 cur = v0; v0 = v1; v1 = v2; if (i + 3 < NV) v2 = ATT_VLD(i + 3);
;                 if (i + 3 < NV) lgkm_pin<3>(cur); else if (i + 2 < NV) lgkm_pin<2>(cur); else if (i + 1 < NV) lgkm_pin<1>(cur); else lgkm_pin<0>(cur);
;                 __builtin_amdgcn_sched_barrier(0);
;                 o[i % (DV / 16)][0] = __builtin_amdgcn_mfma_f32_16x16x32_bf16(cur, pf[0][i / (DV / 16)], o[i % (DV / 16)][0], 0, 0, 0);
;                 o[i % (DV / 16)][1] = __builtin_amdgcn_mfma_f32_16x16x32_bf16(cur, pf[1][i / (DV / 16)], o[i % (DV / 16)][1], 0, 0, 0);
;                 if (i < NV / 2) {
; #pragma unroll
;                     for (int r_ = 0; r_ < EPS; ++r_) { const int e_ = i * EPS + r_; s[2 + (e_ >> 3)][(e_ >> 2) & 1][e_ & 3] = __builtin_amdgcn_exp2f(s[2 + (e_ >> 3)][(e_ >> 2) & 1][e_ & 3]); }
;                 }
;                 __builtin_amdgcn_sched_barrier(0);
;             }
;     ...
;         }
;     }
;     __builtin_amdgcn_s_setprio(0);
.Lbt_skip:
	s_cmp_eq_u32 s32, 1
	s_cbranch_scc0 .LBB0_319
	v_mfma_f32_16x16x32_bf16 v[20:23], v[184:187], v[196:199], v[20:23]
	v_mfma_f32_16x16x32_bf16 v[12:15], v[184:187], v[200:203], v[12:15]
	v_mfma_f32_16x16x32_bf16 v[16:19], v[188:191], v[196:199], v[16:19]
	v_mfma_f32_16x16x32_bf16 v[8:11], v[188:191], v[200:203], v[8:11]
	v_mfma_f32_16x16x32_bf16 v[4:7], v[192:195], v[196:199], v[4:7]
	v_mfma_f32_16x16x32_bf16 v[0:3], v[192:195], v[200:203], v[0:3]
	s_mov_b32 s32, 0
	s_branch .LBB0_319
.LBB0_327:
	s_cmp_eq_u32 s32, 1
	s_cbranch_scc0 .Lbt_exit
	s_waitcnt lgkmcnt(0)
	v_mfma_f32_16x16x32_bf16 v[20:23], v[184:187], v[196:199], v[20:23]
	v_mfma_f32_16x16x32_bf16 v[12:15], v[184:187], v[200:203], v[12:15]
	v_mfma_f32_16x16x32_bf16 v[16:19], v[188:191], v[196:199], v[16:19]
	v_mfma_f32_16x16x32_bf16 v[8:11], v[188:191], v[200:203], v[8:11]
	v_mfma_f32_16x16x32_bf16 v[4:7], v[192:195], v[196:199], v[4:7]
	v_mfma_f32_16x16x32_bf16 v[0:3], v[192:195], v[200:203], v[0:3]
	s_mov_b32 s32, 0
	s_nop 7
	s_nop 7
